# first pre-norm pass: gain/scale/shift vectors of all four column chunks fetched together (was one dependent round trip per chunk)
# speedup vs baseline: 1.0223x; 1.0032x over previous
.LBB0_164:
	s_add_i32 s3, s88, s2
	s_cmpk_lt_i32 s3, 0x4400
	s_cselect_b32 s26, s3, s2
	s_add_u32 s24, s90, s20
	s_addc_u32 s25, s91, s21
	s_add_i32 s27, s2, 0xffffc000
	s_cmpk_gt_i32 s2, 0x3fff
	s_cselect_b32 s25, 0, s25
	s_cselect_b32 s24, s27, s24
	s_cselect_b32 s27, s9, s7
	s_cselect_b32 s28, s8, s6
	s_lshl_b64 s[24:25], s[24:25], 12
	s_add_u32 s24, s28, s24
	s_addc_u32 s25, s27, s25
	v_lshl_add_u64 v[0:1], s[24:25], 0, v[22:23]
	global_load_dwordx4 v[26:29], v[0:1], off
	global_load_dwordx4 v[30:33], v[0:1], off offset:1024
	global_load_dwordx4 v[34:37], v[0:1], off offset:3072
	global_load_dwordx4 v[38:41], v[0:1], off offset:2048
	s_add_i32 s24, s26, 0xffffc000
	s_ashr_i32 s25, s26, 31
	s_cmpk_gt_i32 s26, 0x3fff
	s_cselect_b32 s25, 0, s25
	s_cselect_b32 s24, s24, s26
	s_cselect_b32 s26, s9, s7
	s_cselect_b32 s27, s8, s6
	s_lshl_b64 s[24:25], s[24:25], 12
	s_add_u32 s24, s27, s24
	s_addc_u32 s25, s26, s25
	s_min_i32 s26, s2, 0x4000
	s_ashr_i32 s26, s26, 12
	s_mul_hi_i32 s27, s26, 0x6000
	s_mulk_i32 s26, 0x6000
	s_add_u32 s26, s4, s26
	s_addc_u32 s27, s5, s27
	v_lshl_add_u64 v[54:55], s[26:27], 0, v[22:23]
	v_add_co_u32_e32 v0, vcc, s0, v54
	v_lshl_add_u64 v[58:59], s[24:25], 0, v[22:23]
	s_nop 0
	v_addc_co_u32_e32 v1, vcc, 0, v55, vcc
	global_load_dwordx4 v[42:45], v[0:1], off
	global_load_dwordx4 v[46:49], v[18:19], off
	global_load_dwordx4 v[50:53], v[54:55], off
	global_load_dwordx4 v[64:67], v[18:19], off offset:1024
	global_load_dwordx4 v[68:71], v[0:1], off offset:1024
	global_load_dwordx4 v[72:75], v[54:55], off offset:1024
	global_load_dwordx4 v[76:79], v[18:19], off offset:2048
	global_load_dwordx4 v[80:83], v[0:1], off offset:2048
	global_load_dwordx4 v[84:87], v[54:55], off offset:2048
	global_load_dwordx4 v[88:91], v[18:19], off offset:3072
	global_load_dwordx4 v[92:95], v[0:1], off offset:3072
	global_load_dwordx4 v[96:99], v[54:55], off offset:3072
	s_cmpk_gt_i32 s3, 0x43ff
	s_waitcnt vmcnt(15)
	v_pk_mul_f32 v[0:1], v[28:29], v[28:29]
	v_pk_mul_f32 v[2:3], v[26:27], v[26:27]
	s_waitcnt vmcnt(14)
	v_pk_mul_f32 v[4:5], v[32:33], v[32:33]
	v_pk_mul_f32 v[6:7], v[30:31], v[30:31]
	v_pk_mov_b32 v[12:13], v[2:3], v[0:1] op_sel:[1,0]
	v_mov_b32_e32 v3, v1
	v_pk_mov_b32 v[0:1], v[6:7], v[4:5] op_sel:[1,0]
	v_mov_b32_e32 v7, v5
	s_waitcnt vmcnt(13)
	v_mul_f32_e32 v11, v34, v34
	s_waitcnt vmcnt(12)
	v_mul_f32_e32 v8, v39, v39
	v_mul_f32_e32 v10, v41, v41
	v_pk_add_f32 v[2:3], v[12:13], v[2:3]
	v_pk_add_f32 v[0:1], v[0:1], v[6:7]
	v_mul_f32_e32 v14, v35, v35
	v_mul_f32_e32 v15, v36, v36
	v_mul_f32_e32 v56, v37, v37
	v_pk_fma_f32 v[4:5], v[38:39], v[38:39], v[8:9] op_sel_hi:[1,1,0]
	v_pk_fma_f32 v[8:9], v[40:41], v[40:41], v[10:11] op_sel_hi:[1,1,0]
	v_pk_add_f32 v[2:3], v[2:3], v[2:3] op_sel:[0,1] op_sel_hi:[1,0]
	v_pk_add_f32 v[0:1], v[0:1], v[0:1] op_sel:[0,1] op_sel_hi:[1,0]
	v_mov_b32_e32 v5, v15
	v_mov_b32_e32 v9, v56
	v_mov_b32_e32 v3, v11
	v_mov_b32_e32 v1, v14
	v_pk_add_f32 v[4:5], v[4:5], v[8:9]
	v_pk_add_f32 v[0:1], v[2:3], v[0:1]
	s_waitcnt vmcnt(11)
	v_pk_add_f32 v[44:45], v[44:45], 1.0 op_sel_hi:[1,0]
	v_pk_add_f32 v[0:1], v[0:1], v[4:5]
	v_pk_add_f32 v[42:43], v[42:43], 1.0 op_sel_hi:[1,0]
	v_add_f32_e32 v0, v0, v1
	ds_swizzle_b32 v1, v0 offset:swizzle(SWAP,1)
	global_load_dwordx4 v[12:15], v[58:59], off
	global_load_dwordx4 v[8:11], v[58:59], off offset:1024
	s_waitcnt lgkmcnt(0)
	v_add_f32_e32 v0, v0, v1
	ds_swizzle_b32 v1, v0 offset:swizzle(SWAP,2)
	s_waitcnt lgkmcnt(0)
	v_add_f32_e32 v0, v0, v1
	ds_swizzle_b32 v1, v0 offset:swizzle(SWAP,4)
	s_waitcnt lgkmcnt(0)
	v_add_f32_e32 v0, v0, v1
	ds_swizzle_b32 v1, v0 offset:swizzle(SWAP,8)
	s_waitcnt lgkmcnt(0)
	v_add_f32_e32 v2, v0, v1
	ds_swizzle_b32 v3, v2 offset:swizzle(SWAP,16)
	v_lshl_add_u64 v[0:1], s[14:15], 0, v[20:21]
	v_add_co_u32_e32 v56, vcc, s1, v0
	s_waitcnt lgkmcnt(0)
	v_add_f32_e32 v2, v2, v3
	ds_bpermute_b32 v3, v24, v2
	v_addc_co_u32_e32 v57, vcc, 0, v1, vcc
	s_waitcnt lgkmcnt(0)
	v_add_f32_e32 v0, v2, v3
	v_fmamk_f32 v0, v0, 0x3a800000, v25
	v_rsq_f32_e32 v60, v0
	global_load_dwordx4 v[4:7], v[58:59], off offset:2048
	global_load_dwordx4 v[0:3], v[58:59], off offset:3072
	v_pk_mul_f32 v[28:29], v[28:29], v[60:61] op_sel_hi:[1,0]
	v_pk_mul_f32 v[26:27], v[26:27], v[60:61] op_sel_hi:[1,0]
	s_waitcnt vmcnt(14)
	v_pk_mul_f32 v[28:29], v[48:49], v[28:29]
	v_pk_mul_f32 v[26:27], v[46:47], v[26:27]
	s_waitcnt vmcnt(13)
	v_pk_fma_f32 v[28:29], v[44:45], v[28:29], v[52:53]
	v_pk_fma_f32 v[26:27], v[42:43], v[26:27], v[50:51]
	v_lshl_add_u64 v[50:51], v[54:55], 0, s[22:23]
	v_cvt_pk_bf16_f32 v26, v26, v27
	v_cvt_pk_bf16_f32 v27, v28, v29
	global_store_dwordx2 v[56:57], v[26:27], off
	v_pk_mul_f32 v[32:33], v[32:33], v[60:61] op_sel_hi:[1,0]
	v_pk_mul_f32 v[30:31], v[30:31], v[60:61] op_sel_hi:[1,0]
	v_pk_mul_f32 v[40:41], v[40:41], v[60:61] op_sel_hi:[1,0]
	v_pk_mul_f32 v[38:39], v[38:39], v[60:61] op_sel_hi:[1,0]
	v_pk_mul_f32 v[36:37], v[36:37], v[60:61] op_sel_hi:[1,0]
	v_pk_mul_f32 v[34:35], v[34:35], v[60:61] op_sel_hi:[1,0]
	s_waitcnt vmcnt(12)
	v_pk_mul_f32 v[26:27], v[64:65], v[30:31]
	v_pk_mul_f32 v[28:29], v[66:67], v[32:33]
	s_waitcnt vmcnt(11)
	v_pk_add_f32 v[30:31], v[70:71], 1.0 op_sel_hi:[1,0]
	v_pk_add_f32 v[32:33], v[68:69], 1.0 op_sel_hi:[1,0]
	s_waitcnt vmcnt(10)
	v_pk_fma_f32 v[28:29], v[30:31], v[28:29], v[74:75]
	v_pk_fma_f32 v[26:27], v[32:33], v[26:27], v[72:73]
	s_nop 0
	v_cvt_pk_bf16_f32 v26, v26, v27
	v_cvt_pk_bf16_f32 v27, v28, v29
	global_store_dwordx2 v[56:57], v[26:27], off offset:512
	s_waitcnt vmcnt(9)
	v_pk_mul_f32 v[26:27], v[38:39], v[76:77]
	v_pk_mul_f32 v[28:29], v[40:41], v[78:79]
	s_waitcnt vmcnt(8)
	v_pk_add_f32 v[32:33], v[82:83], 1.0 op_sel_hi:[1,0]
	v_pk_add_f32 v[30:31], v[80:81], 1.0 op_sel_hi:[1,0]
	s_waitcnt vmcnt(7)
	v_pk_fma_f32 v[28:29], v[28:29], v[32:33], v[86:87]
	v_pk_fma_f32 v[26:27], v[26:27], v[30:31], v[84:85]
	s_nop 0
	v_cvt_pk_bf16_f32 v26, v26, v27
	v_cvt_pk_bf16_f32 v27, v28, v29
	global_store_dwordx2 v[56:57], v[26:27], off offset:1024
	s_waitcnt vmcnt(6)
	v_pk_mul_f32 v[26:27], v[34:35], v[88:89]
	v_pk_mul_f32 v[28:29], v[36:37], v[90:91]
	s_waitcnt vmcnt(5)
	v_pk_add_f32 v[32:33], v[94:95], 1.0 op_sel_hi:[1,0]
	v_pk_add_f32 v[30:31], v[92:93], 1.0 op_sel_hi:[1,0]
	s_waitcnt vmcnt(4)
	v_pk_fma_f32 v[28:29], v[28:29], v[32:33], v[98:99]
	v_pk_fma_f32 v[26:27], v[26:27], v[30:31], v[96:97]
	s_nop 0
	v_cvt_pk_bf16_f32 v26, v26, v27
	v_cvt_pk_bf16_f32 v27, v28, v29
	global_store_dwordx2 v[56:57], v[26:27], off offset:1536
	s_cbranch_scc1 .LBB0_163
	s_min_i32 s3, s3, 0x4000
	s_ashr_i32 s3, s3, 12
	s_mul_hi_i32 s25, s3, 0x6000
	s_mulk_i32 s3, 0x6000
	s_add_u32 s24, s4, s3
	s_addc_u32 s25, s5, s25
	v_lshl_add_u64 v[38:39], v[16:17], 2, s[24:25]
	v_add_co_u32_e32 v40, vcc, s0, v38
	global_load_dwordx4 v[26:29], v[18:19], off
	s_nop 0
	v_addc_co_u32_e32 v41, vcc, 0, v39, vcc
	global_load_dwordx4 v[30:33], v[40:41], off
	global_load_dwordx4 v[34:37], v[38:39], off
	global_load_dwordx4 v[136:139], v[18:19], off offset:1024
	global_load_dwordx4 v[140:143], v[40:41], off offset:1024
	global_load_dwordx4 v[144:147], v[38:39], off offset:1024
	global_load_dwordx4 v[148:151], v[18:19], off offset:2048
	global_load_dwordx4 v[152:155], v[40:41], off offset:2048
	global_load_dwordx4 v[156:159], v[38:39], off offset:2048
	global_load_dwordx4 v[160:163], v[18:19], off offset:3072
	global_load_dwordx4 v[164:167], v[40:41], off offset:3072
	global_load_dwordx4 v[168:171], v[38:39], off offset:3072
	s_waitcnt vmcnt(12)
	v_pk_mul_f32 v[40:41], v[14:15], v[14:15]
	v_pk_mul_f32 v[42:43], v[12:13], v[12:13]
	s_nop 0
	v_pk_mov_b32 v[44:45], v[42:43], v[40:41] op_sel:[1,0]
	v_mov_b32_e32 v43, v41
	v_pk_add_f32 v[40:41], v[44:45], v[42:43]
	v_pk_mul_f32 v[42:43], v[10:11], v[10:11]
	v_pk_mul_f32 v[44:45], v[8:9], v[8:9]
	v_pk_add_f32 v[40:41], v[40:41], v[40:41] op_sel:[0,1] op_sel_hi:[1,0]
	v_pk_mov_b32 v[46:47], v[44:45], v[42:43] op_sel:[1,0]
	v_mov_b32_e32 v45, v43
	v_pk_add_f32 v[42:43], v[46:47], v[44:45]
	v_mul_f32_e32 v44, v0, v0
	v_mul_f32_e32 v45, v1, v1
	v_pk_add_f32 v[42:43], v[42:43], v[42:43] op_sel:[0,1] op_sel_hi:[1,0]
	v_mov_b32_e32 v41, v44
	v_mov_b32_e32 v43, v45
	v_pk_add_f32 v[40:41], v[40:41], v[42:43]
	v_mul_f32_e32 v42, v5, v5
	v_mul_f32_e32 v44, v7, v7
	v_mul_f32_e32 v46, v2, v2
	v_mul_f32_e32 v47, v3, v3
	v_pk_fma_f32 v[42:43], v[4:5], v[4:5], v[42:43] op_sel_hi:[1,1,0]
	v_pk_fma_f32 v[44:45], v[6:7], v[6:7], v[44:45] op_sel_hi:[1,1,0]
	v_mov_b32_e32 v43, v46
	v_mov_b32_e32 v45, v47
	v_pk_add_f32 v[42:43], v[42:43], v[44:45]
	s_nop 0
	v_pk_add_f32 v[40:41], v[40:41], v[42:43]
	s_nop 0
	v_add_f32_e32 v40, v40, v41
	ds_swizzle_b32 v41, v40 offset:swizzle(SWAP,1)
	s_waitcnt lgkmcnt(0)
	v_add_f32_e32 v40, v40, v41
	ds_swizzle_b32 v41, v40 offset:swizzle(SWAP,2)
	s_waitcnt lgkmcnt(0)
	v_add_f32_e32 v40, v40, v41
	ds_swizzle_b32 v41, v40 offset:swizzle(SWAP,4)
	s_waitcnt lgkmcnt(0)
	v_add_f32_e32 v40, v40, v41
	ds_swizzle_b32 v41, v40 offset:swizzle(SWAP,8)
	s_waitcnt lgkmcnt(0)
	v_add_f32_e32 v40, v40, v41
	ds_swizzle_b32 v41, v40 offset:swizzle(SWAP,16)
	s_waitcnt lgkmcnt(0)
	v_add_f32_e32 v42, v40, v41
	ds_bpermute_b32 v43, v24, v42
	v_lshl_add_u64 v[40:41], s[18:19], 0, v[20:21]
	v_add_co_u32_e32 v40, vcc, s1, v40
	s_waitcnt lgkmcnt(0)
	v_add_f32_e32 v42, v42, v43
	v_fmamk_f32 v42, v42, 0x3a800000, v25
	v_rsq_f32_e32 v42, v42
	v_addc_co_u32_e32 v41, vcc, 0, v41, vcc
	v_pk_mul_f32 v[14:15], v[14:15], v[42:43] op_sel_hi:[1,0]
	v_pk_mul_f32 v[12:13], v[12:13], v[42:43] op_sel_hi:[1,0]
	v_pk_mul_f32 v[10:11], v[10:11], v[42:43] op_sel_hi:[1,0]
	v_pk_mul_f32 v[8:9], v[8:9], v[42:43] op_sel_hi:[1,0]
	s_waitcnt vmcnt(11)
	v_pk_mul_f32 v[12:13], v[26:27], v[12:13]
	v_pk_mul_f32 v[14:15], v[28:29], v[14:15]
	s_waitcnt vmcnt(10)
	v_pk_add_f32 v[26:27], v[32:33], 1.0 op_sel_hi:[1,0]
	v_pk_add_f32 v[28:29], v[30:31], 1.0 op_sel_hi:[1,0]
	s_waitcnt vmcnt(9)
	v_pk_fma_f32 v[14:15], v[26:27], v[14:15], v[36:37]
	v_pk_fma_f32 v[12:13], v[28:29], v[12:13], v[34:35]
	v_lshl_add_u64 v[34:35], v[38:39], 0, s[22:23]
	v_cvt_pk_bf16_f32 v12, v12, v13
	v_cvt_pk_bf16_f32 v13, v14, v15
	global_store_dwordx2 v[40:41], v[12:13], off
	v_pk_mul_f32 v[6:7], v[6:7], v[42:43] op_sel_hi:[1,0]
	v_pk_mul_f32 v[4:5], v[4:5], v[42:43] op_sel_hi:[1,0]
	v_pk_mul_f32 v[2:3], v[2:3], v[42:43] op_sel_hi:[1,0]
	v_pk_mul_f32 v[0:1], v[0:1], v[42:43] op_sel_hi:[1,0]
	s_waitcnt vmcnt(8)
	v_pk_mul_f32 v[8:9], v[136:137], v[8:9]
	v_pk_mul_f32 v[10:11], v[138:139], v[10:11]
	s_waitcnt vmcnt(7)
	v_pk_add_f32 v[12:13], v[142:143], 1.0 op_sel_hi:[1,0]
	v_pk_add_f32 v[14:15], v[140:141], 1.0 op_sel_hi:[1,0]
	s_waitcnt vmcnt(6)
	v_pk_fma_f32 v[10:11], v[12:13], v[10:11], v[146:147]
	v_pk_fma_f32 v[8:9], v[14:15], v[8:9], v[144:145]
	s_nop 0
	v_cvt_pk_bf16_f32 v8, v8, v9
	v_cvt_pk_bf16_f32 v9, v10, v11
	global_store_dwordx2 v[40:41], v[8:9], off offset:512
	s_waitcnt vmcnt(5)
	v_pk_mul_f32 v[4:5], v[4:5], v[148:149]
	v_pk_mul_f32 v[6:7], v[6:7], v[150:151]
	s_waitcnt vmcnt(4)
	v_pk_add_f32 v[8:9], v[154:155], 1.0 op_sel_hi:[1,0]
	v_pk_add_f32 v[10:11], v[152:153], 1.0 op_sel_hi:[1,0]
	s_waitcnt vmcnt(3)
	v_pk_fma_f32 v[6:7], v[6:7], v[8:9], v[158:159]
	v_pk_fma_f32 v[4:5], v[4:5], v[10:11], v[156:157]
	s_nop 0
	v_cvt_pk_bf16_f32 v4, v4, v5
	v_cvt_pk_bf16_f32 v5, v6, v7
	global_store_dwordx2 v[40:41], v[4:5], off offset:1024
	s_waitcnt vmcnt(2)
	v_pk_mul_f32 v[0:1], v[0:1], v[160:161]
	v_pk_mul_f32 v[2:3], v[2:3], v[162:163]
	s_waitcnt vmcnt(1)
	v_pk_add_f32 v[4:5], v[166:167], 1.0 op_sel_hi:[1,0]
	v_pk_add_f32 v[6:7], v[164:165], 1.0 op_sel_hi:[1,0]
	s_waitcnt vmcnt(0)
	v_pk_fma_f32 v[2:3], v[2:3], v[4:5], v[170:171]
	v_pk_fma_f32 v[0:1], v[0:1], v[6:7], v[168:169]
	s_nop 0
	v_cvt_pk_bf16_f32 v0, v0, v1
	v_cvt_pk_bf16_f32 v1, v2, v3
	global_store_dwordx2 v[40:41], v[0:1], off offset:1536
	s_branch .LBB0_163
